# v42 + removed 32 s_nop pads in GLA log-sigmoid that no longer separate any hazard pair
# baseline (speedup 1.0000x reference)
; DEVI void gla_seq(const Params& p, int l, int item, char* lds) {
;     ...
;     float bcum[16];
;     {
;       float run = 0.f;
; #pragma unroll
;       for (int ii = 0; ii < 16; ++ii) {
;         const float* gr_ = gas + (seg * 16 + ii) * 16;
;         float z = ba;
; #pragma unroll
;         for (int r = 0; r < 16; ++r) z += gr_[r] * w2[r];
;         const float ls = fminf(z, 0.f) - __logf(1.f + __expf(-fabsf(z)));
;         run += ls * (1.f / 16.f);
;         bcum[ii] = run;
;       }
;       segtot[seg * 128 + d] = run;
.LBB0_399:
	ds_read_b128 v[16:19], v127
	ds_read_b128 v[20:23], v127 offset:16
	ds_read_b128 v[24:27], v127 offset:32
	ds_read_b128 v[28:31], v127 offset:48
	s_mov_b32 s29, 0x3f317217
	s_waitcnt lgkmcnt(3)
	v_fma_f32 v16, v106, v16, v122
	v_fmac_f32_e32 v16, v107, v17
	v_fmac_f32_e32 v16, v108, v18
	v_fmac_f32_e32 v16, v109, v19
	s_waitcnt lgkmcnt(2)
	v_fmac_f32_e32 v16, v110, v20
	v_fmac_f32_e32 v16, v111, v21
	v_fmac_f32_e32 v16, v112, v22
	v_fmac_f32_e32 v16, v113, v23
	s_waitcnt lgkmcnt(1)
	v_fmac_f32_e32 v16, v114, v24
	v_fmac_f32_e32 v16, v115, v25
	v_fmac_f32_e32 v16, v116, v26
	v_fmac_f32_e32 v16, v117, v27
	s_waitcnt lgkmcnt(0)
	v_fmac_f32_e32 v16, v118, v28
	v_fmac_f32_e32 v16, v119, v29
	v_fmac_f32_e32 v16, v120, v30
	v_fmac_f32_e32 v16, v121, v31
	v_min_f32_e32 v17, 0, v16
	v_mul_f32_e64 v16, |v16|, s54
	v_exp_f32_e32 v16, v16
	s_mov_b32 s27, 0x7f800000
	v_add_f32_e32 v16, 1.0, v16
	v_log_f32_e32 v16, v16
	s_nop 0
	v_mul_f32_e32 v18, 0x3f317217, v16
	v_fma_f32 v18, v16, s29, -v18
	v_fmac_f32_e32 v18, 0x3377d1cf, v16
	v_fmac_f32_e32 v18, 0x3f317217, v16
	v_sub_f32_e32 v16, v17, v18
	s_mov_b32 s2, 0x3d800000
	v_fma_f32 v20, v16, s2, 0
	ds_read_b128 v[16:19], v127 offset:64
	s_waitcnt lgkmcnt(0)
	v_fma_f32 v21, v106, v16, v122
	v_fmac_f32_e32 v21, v107, v17
	v_fmac_f32_e32 v21, v108, v18
	v_fmac_f32_e32 v21, v109, v19
	ds_read_b128 v[16:19], v127 offset:80
	s_waitcnt lgkmcnt(0)
	v_fmac_f32_e32 v21, v110, v16
	v_fmac_f32_e32 v21, v111, v17
	v_fmac_f32_e32 v21, v112, v18
	v_fmac_f32_e32 v21, v113, v19
	ds_read_b128 v[16:19], v127 offset:96
	s_waitcnt lgkmcnt(0)
	v_fmac_f32_e32 v21, v114, v16
	v_fmac_f32_e32 v21, v115, v17
	v_fmac_f32_e32 v21, v116, v18
	v_fmac_f32_e32 v21, v117, v19
	ds_read_b128 v[16:19], v127 offset:112
	s_waitcnt lgkmcnt(0)
	v_fmac_f32_e32 v21, v118, v16
	v_fmac_f32_e32 v21, v119, v17
	v_fmac_f32_e32 v21, v120, v18
	v_fmac_f32_e32 v21, v121, v19
	v_mul_f32_e64 v17, |v21|, s54
	v_exp_f32_e32 v17, v17
	v_min_f32_e32 v16, 0, v21
	v_add_f32_e32 v17, 1.0, v17
	v_log_f32_e32 v17, v17
	s_nop 0
	v_mul_f32_e32 v18, 0x3f317217, v17
	v_fma_f32 v18, v17, s29, -v18
	v_fmac_f32_e32 v18, 0x3377d1cf, v17
	v_fmac_f32_e32 v18, 0x3f317217, v17
	v_sub_f32_e32 v16, v16, v18
	v_fmamk_f32 v21, v16, 0x3d800000, v20
	ds_read_b128 v[16:19], v127 offset:128
	s_waitcnt lgkmcnt(0)
	v_fma_f32 v22, v106, v16, v122
	v_fmac_f32_e32 v22, v107, v17
	v_fmac_f32_e32 v22, v108, v18
	v_fmac_f32_e32 v22, v109, v19
	ds_read_b128 v[16:19], v127 offset:144
	s_waitcnt lgkmcnt(0)
	v_fmac_f32_e32 v22, v110, v16
	v_fmac_f32_e32 v22, v111, v17
	v_fmac_f32_e32 v22, v112, v18
	v_fmac_f32_e32 v22, v113, v19
	ds_read_b128 v[16:19], v127 offset:160
	s_waitcnt lgkmcnt(0)
	v_fmac_f32_e32 v22, v114, v16
	v_fmac_f32_e32 v22, v115, v17
	v_fmac_f32_e32 v22, v116, v18
	v_fmac_f32_e32 v22, v117, v19
	ds_read_b128 v[16:19], v127 offset:176
	s_waitcnt lgkmcnt(0)
	v_fmac_f32_e32 v22, v118, v16
	v_fmac_f32_e32 v22, v119, v17
	v_fmac_f32_e32 v22, v120, v18
	v_fmac_f32_e32 v22, v121, v19
	v_mul_f32_e64 v17, |v22|, s54
	v_exp_f32_e32 v17, v17
	v_min_f32_e32 v16, 0, v22
	v_add_f32_e32 v17, 1.0, v17
	v_log_f32_e32 v17, v17
	s_nop 0
	v_mul_f32_e32 v18, 0x3f317217, v17
	v_fma_f32 v18, v17, s29, -v18
	v_fmac_f32_e32 v18, 0x3377d1cf, v17
	v_fmac_f32_e32 v18, 0x3f317217, v17
	v_sub_f32_e32 v16, v16, v18
	v_fmamk_f32 v22, v16, 0x3d800000, v21
	ds_read_b128 v[16:19], v127 offset:192
	s_waitcnt lgkmcnt(0)
	v_fma_f32 v23, v106, v16, v122
	v_fmac_f32_e32 v23, v107, v17
	v_fmac_f32_e32 v23, v108, v18
	v_fmac_f32_e32 v23, v109, v19
	ds_read_b128 v[16:19], v127 offset:208
	s_waitcnt lgkmcnt(0)
	v_fmac_f32_e32 v23, v110, v16
	v_fmac_f32_e32 v23, v111, v17
	v_fmac_f32_e32 v23, v112, v18
	v_fmac_f32_e32 v23, v113, v19
	ds_read_b128 v[16:19], v127 offset:224
	s_waitcnt lgkmcnt(0)
	v_fmac_f32_e32 v23, v114, v16
	v_fmac_f32_e32 v23, v115, v17
	v_fmac_f32_e32 v23, v116, v18
	v_fmac_f32_e32 v23, v117, v19
	ds_read_b128 v[16:19], v127 offset:240
	s_waitcnt lgkmcnt(0)
	v_fmac_f32_e32 v23, v118, v16
	v_fmac_f32_e32 v23, v119, v17
	v_fmac_f32_e32 v23, v120, v18
	v_fmac_f32_e32 v23, v121, v19
	v_mul_f32_e64 v17, |v23|, s54
	v_exp_f32_e32 v17, v17
	v_min_f32_e32 v16, 0, v23
	v_add_f32_e32 v17, 1.0, v17
	v_log_f32_e32 v17, v17
	s_nop 0
	v_mul_f32_e32 v18, 0x3f317217, v17
	v_fma_f32 v18, v17, s29, -v18
	v_fmac_f32_e32 v18, 0x3377d1cf, v17
	v_fmac_f32_e32 v18, 0x3f317217, v17
	v_sub_f32_e32 v16, v16, v18
	v_fmamk_f32 v23, v16, 0x3d800000, v22
	ds_read_b128 v[16:19], v127 offset:256
	s_waitcnt lgkmcnt(0)
	v_fma_f32 v24, v106, v16, v122
	v_fmac_f32_e32 v24, v107, v17
	v_fmac_f32_e32 v24, v108, v18
	v_fmac_f32_e32 v24, v109, v19
	ds_read_b128 v[16:19], v127 offset:272
	s_waitcnt lgkmcnt(0)
	v_fmac_f32_e32 v24, v110, v16
	v_fmac_f32_e32 v24, v111, v17
	v_fmac_f32_e32 v24, v112, v18
	v_fmac_f32_e32 v24, v113, v19
	ds_read_b128 v[16:19], v127 offset:288
	s_waitcnt lgkmcnt(0)
	v_fmac_f32_e32 v24, v114, v16
	v_fmac_f32_e32 v24, v115, v17
	v_fmac_f32_e32 v24, v116, v18
	v_fmac_f32_e32 v24, v117, v19
	ds_read_b128 v[16:19], v127 offset:304
	s_waitcnt lgkmcnt(0)
	v_fmac_f32_e32 v24, v118, v16
	v_fmac_f32_e32 v24, v119, v17
	v_fmac_f32_e32 v24, v120, v18
	v_fmac_f32_e32 v24, v121, v19
	v_mul_f32_e64 v17, |v24|, s54
	v_exp_f32_e32 v17, v17
	v_min_f32_e32 v16, 0, v24
	v_add_f32_e32 v17, 1.0, v17
	v_log_f32_e32 v17, v17
	s_nop 0
	v_mul_f32_e32 v18, 0x3f317217, v17
	v_fma_f32 v18, v17, s29, -v18
	v_fmac_f32_e32 v18, 0x3377d1cf, v17
	v_fmac_f32_e32 v18, 0x3f317217, v17
	v_sub_f32_e32 v16, v16, v18
	v_fmamk_f32 v24, v16, 0x3d800000, v23
	ds_read_b128 v[16:19], v127 offset:320
	s_waitcnt lgkmcnt(0)
; DEVI void gla_seq(const Params& p, int l, int item, char* lds) {
;     ...
;       for (int ii = 0; ii < 16; ++ii) {
;         const float* gr_ = gas + (seg * 16 + ii) * 16;
;         float z = ba;
; #pragma unroll
;         for (int r = 0; r < 16; ++r) z += gr_[r] * w2[r];
;         const float ls = fminf(z, 0.f) - __logf(1.f + __expf(-fabsf(z)));
;         run += ls * (1.f / 16.f);
;         bcum[ii] = run;
;       }
	v_fma_f32 v25, v106, v16, v122
	v_fmac_f32_e32 v25, v107, v17
	v_fmac_f32_e32 v25, v108, v18
	v_fmac_f32_e32 v25, v109, v19
	ds_read_b128 v[16:19], v127 offset:336
	s_waitcnt lgkmcnt(0)
	v_fmac_f32_e32 v25, v110, v16
	v_fmac_f32_e32 v25, v111, v17
	v_fmac_f32_e32 v25, v112, v18
	v_fmac_f32_e32 v25, v113, v19
	ds_read_b128 v[16:19], v127 offset:352
	s_waitcnt lgkmcnt(0)
	v_fmac_f32_e32 v25, v114, v16
	v_fmac_f32_e32 v25, v115, v17
	v_fmac_f32_e32 v25, v116, v18
	v_fmac_f32_e32 v25, v117, v19
	ds_read_b128 v[16:19], v127 offset:368
	s_waitcnt lgkmcnt(0)
	v_fmac_f32_e32 v25, v118, v16
	v_fmac_f32_e32 v25, v119, v17
	v_fmac_f32_e32 v25, v120, v18
	v_fmac_f32_e32 v25, v121, v19
	v_mul_f32_e64 v17, |v25|, s54
	v_exp_f32_e32 v17, v17
	v_min_f32_e32 v16, 0, v25
	v_add_f32_e32 v17, 1.0, v17
	v_log_f32_e32 v17, v17
	s_nop 0
	v_mul_f32_e32 v18, 0x3f317217, v17
	v_fma_f32 v18, v17, s29, -v18
	v_fmac_f32_e32 v18, 0x3377d1cf, v17
	v_fmac_f32_e32 v18, 0x3f317217, v17
	v_sub_f32_e32 v16, v16, v18
	v_fmamk_f32 v25, v16, 0x3d800000, v24
	ds_read_b128 v[16:19], v127 offset:384
	s_waitcnt lgkmcnt(0)
	v_fma_f32 v26, v106, v16, v122
	v_fmac_f32_e32 v26, v107, v17
	v_fmac_f32_e32 v26, v108, v18
	v_fmac_f32_e32 v26, v109, v19
	ds_read_b128 v[16:19], v127 offset:400
	s_waitcnt lgkmcnt(0)
	v_fmac_f32_e32 v26, v110, v16
	v_fmac_f32_e32 v26, v111, v17
	v_fmac_f32_e32 v26, v112, v18
	v_fmac_f32_e32 v26, v113, v19
	ds_read_b128 v[16:19], v127 offset:416
	s_waitcnt lgkmcnt(0)
	v_fmac_f32_e32 v26, v114, v16
	v_fmac_f32_e32 v26, v115, v17
	v_fmac_f32_e32 v26, v116, v18
	v_fmac_f32_e32 v26, v117, v19
	ds_read_b128 v[16:19], v127 offset:432
	s_waitcnt lgkmcnt(0)
	v_fmac_f32_e32 v26, v118, v16
	v_fmac_f32_e32 v26, v119, v17
	v_fmac_f32_e32 v26, v120, v18
	v_fmac_f32_e32 v26, v121, v19
	v_mul_f32_e64 v17, |v26|, s54
	v_exp_f32_e32 v17, v17
	v_min_f32_e32 v16, 0, v26
	v_add_f32_e32 v17, 1.0, v17
	v_log_f32_e32 v17, v17
	s_nop 0
	v_mul_f32_e32 v18, 0x3f317217, v17
	v_fma_f32 v18, v17, s29, -v18
	v_fmac_f32_e32 v18, 0x3377d1cf, v17
	v_fmac_f32_e32 v18, 0x3f317217, v17
	v_sub_f32_e32 v16, v16, v18
	v_fmamk_f32 v26, v16, 0x3d800000, v25
	ds_read_b128 v[16:19], v127 offset:448
	s_waitcnt lgkmcnt(0)
	v_fma_f32 v27, v106, v16, v122
	v_fmac_f32_e32 v27, v107, v17
	v_fmac_f32_e32 v27, v108, v18
	v_fmac_f32_e32 v27, v109, v19
	ds_read_b128 v[16:19], v127 offset:464
	s_waitcnt lgkmcnt(0)
	v_fmac_f32_e32 v27, v110, v16
	v_fmac_f32_e32 v27, v111, v17
	v_fmac_f32_e32 v27, v112, v18
	v_fmac_f32_e32 v27, v113, v19
	ds_read_b128 v[16:19], v127 offset:480
	s_waitcnt lgkmcnt(0)
	v_fmac_f32_e32 v27, v114, v16
	v_fmac_f32_e32 v27, v115, v17
	v_fmac_f32_e32 v27, v116, v18
	v_fmac_f32_e32 v27, v117, v19
	ds_read_b128 v[16:19], v127 offset:496
	s_waitcnt lgkmcnt(0)
	v_fmac_f32_e32 v27, v118, v16
	v_fmac_f32_e32 v27, v119, v17
	v_fmac_f32_e32 v27, v120, v18
	v_fmac_f32_e32 v27, v121, v19
	v_mul_f32_e64 v17, |v27|, s54
	v_exp_f32_e32 v17, v17
	v_min_f32_e32 v16, 0, v27
	v_add_f32_e32 v17, 1.0, v17
	v_log_f32_e32 v17, v17
	s_nop 0
	v_mul_f32_e32 v18, 0x3f317217, v17
	v_fma_f32 v18, v17, s29, -v18
	v_fmac_f32_e32 v18, 0x3377d1cf, v17
	v_fmac_f32_e32 v18, 0x3f317217, v17
	v_sub_f32_e32 v16, v16, v18
	v_fmamk_f32 v27, v16, 0x3d800000, v26
	ds_read_b128 v[16:19], v127 offset:512
	s_waitcnt lgkmcnt(0)
	v_fma_f32 v28, v106, v16, v122
	v_fmac_f32_e32 v28, v107, v17
	v_fmac_f32_e32 v28, v108, v18
	v_fmac_f32_e32 v28, v109, v19
	ds_read_b128 v[16:19], v127 offset:528
	s_waitcnt lgkmcnt(0)
	v_fmac_f32_e32 v28, v110, v16
	v_fmac_f32_e32 v28, v111, v17
	v_fmac_f32_e32 v28, v112, v18
	v_fmac_f32_e32 v28, v113, v19
	ds_read_b128 v[16:19], v127 offset:544
	s_waitcnt lgkmcnt(0)
	v_fmac_f32_e32 v28, v114, v16
	v_fmac_f32_e32 v28, v115, v17
	v_fmac_f32_e32 v28, v116, v18
	v_fmac_f32_e32 v28, v117, v19
	ds_read_b128 v[16:19], v127 offset:560
	s_waitcnt lgkmcnt(0)
	v_fmac_f32_e32 v28, v118, v16
	v_fmac_f32_e32 v28, v119, v17
	v_fmac_f32_e32 v28, v120, v18
	v_fmac_f32_e32 v28, v121, v19
	v_mul_f32_e64 v17, |v28|, s54
	v_exp_f32_e32 v17, v17
	v_min_f32_e32 v16, 0, v28
	v_add_f32_e32 v17, 1.0, v17
	v_log_f32_e32 v17, v17
	s_nop 0
	v_mul_f32_e32 v18, 0x3f317217, v17
	v_fma_f32 v18, v17, s29, -v18
	v_fmac_f32_e32 v18, 0x3377d1cf, v17
	v_fmac_f32_e32 v18, 0x3f317217, v17
	v_sub_f32_e32 v16, v16, v18
	v_fmamk_f32 v28, v16, 0x3d800000, v27
	ds_read_b128 v[16:19], v127 offset:576
	s_waitcnt lgkmcnt(0)
	v_fma_f32 v29, v106, v16, v122
	v_fmac_f32_e32 v29, v107, v17
	v_fmac_f32_e32 v29, v108, v18
	v_fmac_f32_e32 v29, v109, v19
	ds_read_b128 v[16:19], v127 offset:592
	s_waitcnt lgkmcnt(0)
	v_fmac_f32_e32 v29, v110, v16
	v_fmac_f32_e32 v29, v111, v17
	v_fmac_f32_e32 v29, v112, v18
	v_fmac_f32_e32 v29, v113, v19
	ds_read_b128 v[16:19], v127 offset:608
	s_waitcnt lgkmcnt(0)
	v_fmac_f32_e32 v29, v114, v16
	v_fmac_f32_e32 v29, v115, v17
	v_fmac_f32_e32 v29, v116, v18
	v_fmac_f32_e32 v29, v117, v19
	ds_read_b128 v[16:19], v127 offset:624
	s_waitcnt lgkmcnt(0)
	v_fmac_f32_e32 v29, v118, v16
	v_fmac_f32_e32 v29, v119, v17
	v_fmac_f32_e32 v29, v120, v18
	v_fmac_f32_e32 v29, v121, v19
	v_mul_f32_e64 v17, |v29|, s54
	v_exp_f32_e32 v17, v17
	v_min_f32_e32 v16, 0, v29
	v_add_f32_e32 v17, 1.0, v17
	v_log_f32_e32 v17, v17
	s_nop 0
	v_mul_f32_e32 v18, 0x3f317217, v17
	v_fma_f32 v18, v17, s29, -v18
	v_fmac_f32_e32 v18, 0x3377d1cf, v17
	v_fmac_f32_e32 v18, 0x3f317217, v17
	v_sub_f32_e32 v16, v16, v18
	v_fmamk_f32 v29, v16, 0x3d800000, v28
	ds_read_b128 v[16:19], v127 offset:640
	s_waitcnt lgkmcnt(0)
	v_fma_f32 v30, v106, v16, v122
	v_fmac_f32_e32 v30, v107, v17
	v_fmac_f32_e32 v30, v108, v18
	v_fmac_f32_e32 v30, v109, v19
	ds_read_b128 v[16:19], v127 offset:656
	s_waitcnt lgkmcnt(0)
; DEVI void gla_seq(const Params& p, int l, int item, char* lds) {
;     ...
;       for (int ii = 0; ii < 16; ++ii) {
;         const float* gr_ = gas + (seg * 16 + ii) * 16;
;         float z = ba;
; #pragma unroll
;         for (int r = 0; r < 16; ++r) z += gr_[r] * w2[r];
;         const float ls = fminf(z, 0.f) - __logf(1.f + __expf(-fabsf(z)));
;         run += ls * (1.f / 16.f);
;         bcum[ii] = run;
;       }
;       segtot[seg * 128 + d] = run;
;     }
;     __syncthreads();
	v_fmac_f32_e32 v30, v110, v16
	v_fmac_f32_e32 v30, v111, v17
	v_fmac_f32_e32 v30, v112, v18
	v_fmac_f32_e32 v30, v113, v19
	ds_read_b128 v[16:19], v127 offset:672
	s_waitcnt lgkmcnt(0)
	v_fmac_f32_e32 v30, v114, v16
	v_fmac_f32_e32 v30, v115, v17
	v_fmac_f32_e32 v30, v116, v18
	v_fmac_f32_e32 v30, v117, v19
	ds_read_b128 v[16:19], v127 offset:688
	s_waitcnt lgkmcnt(0)
	v_fmac_f32_e32 v30, v118, v16
	v_fmac_f32_e32 v30, v119, v17
	v_fmac_f32_e32 v30, v120, v18
	v_fmac_f32_e32 v30, v121, v19
	v_mul_f32_e64 v17, |v30|, s54
	v_exp_f32_e32 v17, v17
	v_min_f32_e32 v16, 0, v30
	v_add_f32_e32 v17, 1.0, v17
	v_log_f32_e32 v17, v17
	s_nop 0
	v_mul_f32_e32 v18, 0x3f317217, v17
	v_fma_f32 v18, v17, s29, -v18
	v_fmac_f32_e32 v18, 0x3377d1cf, v17
	v_fmac_f32_e32 v18, 0x3f317217, v17
	v_sub_f32_e32 v16, v16, v18
	v_fmamk_f32 v30, v16, 0x3d800000, v29
	ds_read_b128 v[16:19], v127 offset:704
	s_waitcnt lgkmcnt(0)
	v_fma_f32 v31, v106, v16, v122
	v_fmac_f32_e32 v31, v107, v17
	v_fmac_f32_e32 v31, v108, v18
	v_fmac_f32_e32 v31, v109, v19
	ds_read_b128 v[16:19], v127 offset:720
	s_waitcnt lgkmcnt(0)
	v_fmac_f32_e32 v31, v110, v16
	v_fmac_f32_e32 v31, v111, v17
	v_fmac_f32_e32 v31, v112, v18
	v_fmac_f32_e32 v31, v113, v19
	ds_read_b128 v[16:19], v127 offset:736
	s_waitcnt lgkmcnt(0)
	v_fmac_f32_e32 v31, v114, v16
	v_fmac_f32_e32 v31, v115, v17
	v_fmac_f32_e32 v31, v116, v18
	v_fmac_f32_e32 v31, v117, v19
	ds_read_b128 v[16:19], v127 offset:752
	s_waitcnt lgkmcnt(0)
	v_fmac_f32_e32 v31, v118, v16
	v_fmac_f32_e32 v31, v119, v17
	v_fmac_f32_e32 v31, v120, v18
	v_fmac_f32_e32 v31, v121, v19
	v_mul_f32_e64 v17, |v31|, s54
	v_exp_f32_e32 v17, v17
	v_min_f32_e32 v16, 0, v31
	v_add_f32_e32 v17, 1.0, v17
	v_log_f32_e32 v17, v17
	s_nop 0
	v_mul_f32_e32 v18, 0x3f317217, v17
	v_fma_f32 v18, v17, s29, -v18
	v_fmac_f32_e32 v18, 0x3377d1cf, v17
	v_fmac_f32_e32 v18, 0x3f317217, v17
	v_sub_f32_e32 v16, v16, v18
	v_fmamk_f32 v31, v16, 0x3d800000, v30
	ds_read_b128 v[16:19], v127 offset:768
	s_waitcnt lgkmcnt(0)
	v_fma_f32 v32, v106, v16, v122
	v_fmac_f32_e32 v32, v107, v17
	v_fmac_f32_e32 v32, v108, v18
	v_fmac_f32_e32 v32, v109, v19
	ds_read_b128 v[16:19], v127 offset:784
	s_waitcnt lgkmcnt(0)
	v_fmac_f32_e32 v32, v110, v16
	v_fmac_f32_e32 v32, v111, v17
	v_fmac_f32_e32 v32, v112, v18
	v_fmac_f32_e32 v32, v113, v19
	ds_read_b128 v[16:19], v127 offset:800
	s_waitcnt lgkmcnt(0)
	v_fmac_f32_e32 v32, v114, v16
	v_fmac_f32_e32 v32, v115, v17
	v_fmac_f32_e32 v32, v116, v18
	v_fmac_f32_e32 v32, v117, v19
	ds_read_b128 v[16:19], v127 offset:816
	s_waitcnt lgkmcnt(0)
	v_fmac_f32_e32 v32, v118, v16
	v_fmac_f32_e32 v32, v119, v17
	v_fmac_f32_e32 v32, v120, v18
	v_fmac_f32_e32 v32, v121, v19
	v_mul_f32_e64 v17, |v32|, s54
	v_exp_f32_e32 v17, v17
	v_min_f32_e32 v16, 0, v32
	v_add_f32_e32 v17, 1.0, v17
	v_log_f32_e32 v17, v17
	s_nop 0
	v_mul_f32_e32 v18, 0x3f317217, v17
	v_fma_f32 v18, v17, s29, -v18
	v_fmac_f32_e32 v18, 0x3377d1cf, v17
	v_fmac_f32_e32 v18, 0x3f317217, v17
	v_sub_f32_e32 v16, v16, v18
	v_fmamk_f32 v32, v16, 0x3d800000, v31
	ds_read_b128 v[16:19], v127 offset:832
	s_waitcnt lgkmcnt(0)
	v_fma_f32 v33, v106, v16, v122
	v_fmac_f32_e32 v33, v107, v17
	v_fmac_f32_e32 v33, v108, v18
	v_fmac_f32_e32 v33, v109, v19
	ds_read_b128 v[16:19], v127 offset:848
	s_waitcnt lgkmcnt(0)
	v_fmac_f32_e32 v33, v110, v16
	v_fmac_f32_e32 v33, v111, v17
	v_fmac_f32_e32 v33, v112, v18
	v_fmac_f32_e32 v33, v113, v19
	ds_read_b128 v[16:19], v127 offset:864
	s_waitcnt lgkmcnt(0)
	v_fmac_f32_e32 v33, v114, v16
	v_fmac_f32_e32 v33, v115, v17
	v_fmac_f32_e32 v33, v116, v18
	v_fmac_f32_e32 v33, v117, v19
	ds_read_b128 v[16:19], v127 offset:880
	s_waitcnt lgkmcnt(0)
	v_fmac_f32_e32 v33, v118, v16
	v_fmac_f32_e32 v33, v119, v17
	v_fmac_f32_e32 v33, v120, v18
	v_fmac_f32_e32 v33, v121, v19
	v_mul_f32_e64 v17, |v33|, s54
	v_exp_f32_e32 v17, v17
	v_min_f32_e32 v16, 0, v33
	v_add_f32_e32 v17, 1.0, v17
	v_log_f32_e32 v17, v17
	s_nop 0
	v_mul_f32_e32 v18, 0x3f317217, v17
	v_fma_f32 v18, v17, s29, -v18
	v_fmac_f32_e32 v18, 0x3377d1cf, v17
	v_fmac_f32_e32 v18, 0x3f317217, v17
	v_sub_f32_e32 v16, v16, v18
	v_fmamk_f32 v33, v16, 0x3d800000, v32
	ds_read_b128 v[16:19], v127 offset:896
	s_waitcnt lgkmcnt(0)
	v_fma_f32 v34, v106, v16, v122
	v_fmac_f32_e32 v34, v107, v17
	v_fmac_f32_e32 v34, v108, v18
	v_fmac_f32_e32 v34, v109, v19
	ds_read_b128 v[16:19], v127 offset:912
	s_waitcnt lgkmcnt(0)
	v_fmac_f32_e32 v34, v110, v16
	v_fmac_f32_e32 v34, v111, v17
	v_fmac_f32_e32 v34, v112, v18
	v_fmac_f32_e32 v34, v113, v19
	ds_read_b128 v[16:19], v127 offset:928
	s_waitcnt lgkmcnt(0)
	v_fmac_f32_e32 v34, v114, v16
	v_fmac_f32_e32 v34, v115, v17
	v_fmac_f32_e32 v34, v116, v18
	v_fmac_f32_e32 v34, v117, v19
	ds_read_b128 v[16:19], v127 offset:944
	s_waitcnt lgkmcnt(0)
	v_fmac_f32_e32 v34, v118, v16
	v_fmac_f32_e32 v34, v119, v17
	v_fmac_f32_e32 v34, v120, v18
	v_fmac_f32_e32 v34, v121, v19
	v_mul_f32_e64 v17, |v34|, s54
	v_exp_f32_e32 v17, v17
	v_min_f32_e32 v16, 0, v34
	v_add_f32_e32 v17, 1.0, v17
	v_log_f32_e32 v17, v17
	s_nop 0
	v_mul_f32_e32 v18, 0x3f317217, v17
	v_fma_f32 v18, v17, s29, -v18
	v_fmac_f32_e32 v18, 0x3377d1cf, v17
	v_fmac_f32_e32 v18, 0x3f317217, v17
	v_sub_f32_e32 v16, v16, v18
	v_fmamk_f32 v34, v16, 0x3d800000, v33
	ds_read_b128 v[16:19], v127 offset:960
	s_waitcnt lgkmcnt(0)
	v_fma_f32 v35, v106, v16, v122
	v_fmac_f32_e32 v35, v107, v17
	v_fmac_f32_e32 v35, v108, v18
	v_fmac_f32_e32 v35, v109, v19
	ds_read_b128 v[16:19], v127 offset:976
	s_waitcnt lgkmcnt(0)
	v_fmac_f32_e32 v35, v110, v16
	v_fmac_f32_e32 v35, v111, v17
	v_fmac_f32_e32 v35, v112, v18
	v_fmac_f32_e32 v35, v113, v19
	ds_read_b128 v[16:19], v127 offset:992
	s_waitcnt lgkmcnt(0)
	v_fmac_f32_e32 v35, v114, v16
	v_fmac_f32_e32 v35, v115, v17
	v_fmac_f32_e32 v35, v116, v18
	v_fmac_f32_e32 v35, v117, v19
	ds_read_b128 v[16:19], v127 offset:1008
	s_waitcnt lgkmcnt(0)
	v_fmac_f32_e32 v35, v118, v16
	v_fmac_f32_e32 v35, v119, v17
	v_fmac_f32_e32 v35, v120, v18
	v_fmac_f32_e32 v35, v121, v19
	v_mul_f32_e64 v17, |v35|, s54
	v_exp_f32_e32 v17, v17
	v_min_f32_e32 v16, 0, v35
	v_add_f32_e32 v17, 1.0, v17
	v_log_f32_e32 v17, v17
	s_nop 0
	v_mul_f32_e32 v18, 0x3f317217, v17
	v_fma_f32 v18, v17, s29, -v18
	v_fmac_f32_e32 v18, 0x3377d1cf, v17
	v_fmac_f32_e32 v18, 0x3f317217, v17
	v_sub_f32_e32 v16, v16, v18
	v_fmamk_f32 v35, v16, 0x3d800000, v34
	ds_write_b32 v128, v35
	s_waitcnt lgkmcnt(0)
	s_barrier
; DEVI u16 f2bf(float f) { return (u16)(cvtpk(f, 0.f) & 0xffffu); }
; DEVI float bf2f(u16 h) { return __uint_as_float(((unsigned)h) << 16); }
; DEVI void gla_seq(const Params& p, int l, int item, char* lds) {
;     ...
;     {
;       float pre = 0.f, tot = 0.f;
; #pragma unroll
;       for (int s_ = 0; s_ < 4; ++s_) { const float v = segtot[s_ * 128 + d]; tot += v; if (s_ < seg) pre += v; }
;       const float etot = __expf(tot);
;       if (seg == 0) ebl[d] = etot;
; #pragma unroll
;       for (int ii = 0; ii < 16; ++ii) {
;         const int i = seg * 16 + ii;
;         const float bb = bcum[ii] + pre;
;         const int so = i * 256 + (((d >> 3) ^ (i & 7)) << 4) + (d & 7) * 2;
;         const float q = bf2f(*(const u16*)(qs + so)), k = bf2f(*(const u16*)(ks + so));
;         const float eb = __expf(bb), ieb = __frcp_rn(eb);
;         *(u16*)(qs + so) = f2bf(q * eb);
;         *(u16*)(ks + so) = f2bf(k * ieb);
;         *(u16*)(kT + d * 144 + i * 2) = f2bf(k * (etot * ieb));
;       }
	ds_read2st64_b32 v[16:17], v129 offset1:2
	ds_read2st64_b32 v[18:19], v129 offset0:4 offset1:6
	s_waitcnt lgkmcnt(1)
	v_add_f32_e32 v36, 0, v16
	v_add_f32_e32 v16, v36, v17
	s_waitcnt lgkmcnt(0)
	v_add_f32_e32 v16, v16, v18
	v_add_f32_e32 v16, v16, v19
	v_mul_f32_e32 v16, 0x3fb8aa3b, v16
	v_exp_f32_e32 v16, v16
	s_and_saveexec_b64 s[2:3], s[6:7]
	ds_write_b32 v136, v16
	s_or_b64 exec, exec, s[2:3]
	v_cndmask_b32_e64 v36, 0, v36, s[10:11]
	v_add_f32_e32 v17, v17, v36
	v_cndmask_b32_e64 v17, v36, v17, s[12:13]
	v_add_f32_e32 v18, v18, v17
	v_cndmask_b32_e64 v17, v17, v18, s[14:15]
	v_add_f32_e32 v18, v19, v17
	v_cndmask_b32_e64 v17, v17, v18, s[16:17]
	v_add_f32_e32 v18, v20, v17
	v_mul_f32_e32 v18, 0x3fb8aa3b, v18
	v_exp_f32_e64 v36, -v18
	v_exp_f32_e32 v18, v18
	ds_read_u16 v19, v154
	ds_read_u16 v20, v154 offset:16384
	v_add_u32_e32 v187, v133, v131
	s_waitcnt lgkmcnt(1)
	v_lshlrev_b32_e32 v19, 16, v19
	s_waitcnt lgkmcnt(0)
	v_lshlrev_b32_e32 v20, 16, v20
	v_mul_f32_e32 v18, v18, v19
	v_cvt_pk_bf16_f32 v18, v18, s0
	ds_write_b16 v154, v18
	v_mul_f32_e32 v18, v36, v20
	v_cvt_pk_bf16_f32 v18, v18, s0
	ds_write_b16 v154, v18 offset:16384
	v_mul_f32_e32 v18, v16, v36
	v_mul_f32_e32 v18, v18, v20
	v_cvt_pk_bf16_f32 v18, v18, s0
	v_add_u32_e32 v19, v130, v132
	ds_write_b16 v19, v18 offset:32768
	v_add_f32_e32 v18, v21, v17
	v_mul_f32_e32 v18, 0x3fb8aa3b, v18
	v_exp_f32_e64 v21, -v18
	v_exp_f32_e32 v18, v18
	ds_read_u16 v19, v155
	ds_read_u16 v20, v155 offset:16384
	s_waitcnt lgkmcnt(1)
	v_lshlrev_b32_e32 v19, 16, v19
	s_waitcnt lgkmcnt(0)
	v_lshlrev_b32_e32 v20, 16, v20
	v_mul_f32_e32 v18, v18, v19
	v_cvt_pk_bf16_f32 v18, v18, s0
	ds_write_b16 v155, v18
	v_mul_f32_e32 v18, v21, v20
	v_cvt_pk_bf16_f32 v18, v18, s0
	ds_write_b16 v155, v18 offset:16384
	v_mul_f32_e32 v18, v16, v21
	v_mul_f32_e32 v18, v18, v20
	v_cvt_pk_bf16_f32 v18, v18, s0
	ds_write_b16 v156, v18 offset:32768
	v_add_f32_e32 v18, v22, v17
	v_mul_f32_e32 v18, 0x3fb8aa3b, v18
	v_exp_f32_e64 v21, -v18
	v_exp_f32_e32 v18, v18
	ds_read_u16 v19, v157
	ds_read_u16 v20, v157 offset:16384
	s_waitcnt lgkmcnt(1)
	v_lshlrev_b32_e32 v19, 16, v19
	s_waitcnt lgkmcnt(0)
	v_lshlrev_b32_e32 v20, 16, v20
	v_mul_f32_e32 v18, v18, v19
	v_cvt_pk_bf16_f32 v18, v18, s0
	ds_write_b16 v157, v18
	v_mul_f32_e32 v18, v21, v20
	v_cvt_pk_bf16_f32 v18, v18, s0
	ds_write_b16 v157, v18 offset:16384
	v_mul_f32_e32 v18, v16, v21
	v_mul_f32_e32 v18, v18, v20
	v_cvt_pk_bf16_f32 v18, v18, s0
	ds_write_b16 v158, v18 offset:32768
	v_add_f32_e32 v18, v23, v17
	v_mul_f32_e32 v18, 0x3fb8aa3b, v18
	v_exp_f32_e64 v21, -v18
	v_exp_f32_e32 v18, v18
	ds_read_u16 v19, v159
	ds_read_u16 v20, v159 offset:16384
	s_waitcnt lgkmcnt(1)
	v_lshlrev_b32_e32 v19, 16, v19
	s_waitcnt lgkmcnt(0)
	v_lshlrev_b32_e32 v20, 16, v20
	v_mul_f32_e32 v18, v18, v19
	v_cvt_pk_bf16_f32 v18, v18, s0
	ds_write_b16 v159, v18
	v_mul_f32_e32 v18, v21, v20
	v_cvt_pk_bf16_f32 v18, v18, s0
	ds_write_b16 v159, v18 offset:16384
	v_mul_f32_e32 v18, v16, v21
	v_mul_f32_e32 v18, v18, v20
	v_cvt_pk_bf16_f32 v18, v18, s0
	ds_write_b16 v160, v18 offset:32768
	v_add_f32_e32 v18, v24, v17
	v_mul_f32_e32 v18, 0x3fb8aa3b, v18
	v_exp_f32_e64 v21, -v18
	v_exp_f32_e32 v18, v18
	ds_read_u16 v19, v161
	ds_read_u16 v20, v161 offset:16384
	s_waitcnt lgkmcnt(1)
	v_lshlrev_b32_e32 v19, 16, v19
	s_waitcnt lgkmcnt(0)
	v_lshlrev_b32_e32 v20, 16, v20
	v_mul_f32_e32 v18, v18, v19
	v_cvt_pk_bf16_f32 v18, v18, s0
	ds_write_b16 v161, v18
	v_mul_f32_e32 v18, v21, v20
	v_cvt_pk_bf16_f32 v18, v18, s0
	ds_write_b16 v161, v18 offset:16384
	v_mul_f32_e32 v18, v16, v21
	v_mul_f32_e32 v18, v18, v20
	v_cvt_pk_bf16_f32 v18, v18, s0
	ds_write_b16 v162, v18 offset:32768
	v_add_f32_e32 v18, v25, v17
	v_mul_f32_e32 v18, 0x3fb8aa3b, v18
	v_exp_f32_e64 v21, -v18
	v_exp_f32_e32 v18, v18
	ds_read_u16 v19, v163
	ds_read_u16 v20, v163 offset:16384
	s_waitcnt lgkmcnt(1)
	v_lshlrev_b32_e32 v19, 16, v19
	s_waitcnt lgkmcnt(0)
	v_lshlrev_b32_e32 v20, 16, v20
	v_mul_f32_e32 v18, v18, v19
	v_cvt_pk_bf16_f32 v18, v18, s0
	ds_write_b16 v163, v18
	v_mul_f32_e32 v18, v21, v20
	v_cvt_pk_bf16_f32 v18, v18, s0
	ds_write_b16 v163, v18 offset:16384
	v_mul_f32_e32 v18, v16, v21
	v_mul_f32_e32 v18, v18, v20
	v_cvt_pk_bf16_f32 v18, v18, s0
	ds_write_b16 v164, v18 offset:32768
	v_add_f32_e32 v18, v26, v17
	v_mul_f32_e32 v18, 0x3fb8aa3b, v18
	v_exp_f32_e64 v21, -v18
	v_exp_f32_e32 v18, v18
	ds_read_u16 v19, v165
	ds_read_u16 v20, v165 offset:16384
	s_waitcnt lgkmcnt(1)
	v_lshlrev_b32_e32 v19, 16, v19
	s_waitcnt lgkmcnt(0)
	v_lshlrev_b32_e32 v20, 16, v20
	v_mul_f32_e32 v18, v18, v19
	v_cvt_pk_bf16_f32 v18, v18, s0
	ds_write_b16 v165, v18
	v_mul_f32_e32 v18, v21, v20
	v_cvt_pk_bf16_f32 v18, v18, s0
	ds_write_b16 v165, v18 offset:16384
	v_mul_f32_e32 v18, v16, v21
	v_mul_f32_e32 v18, v18, v20
	v_cvt_pk_bf16_f32 v18, v18, s0
	ds_write_b16 v166, v18 offset:32768
	v_add_f32_e32 v18, v27, v17
	v_mul_f32_e32 v18, 0x3fb8aa3b, v18
	v_exp_f32_e64 v21, -v18
	v_exp_f32_e32 v18, v18
	ds_read_u16 v19, v167
	ds_read_u16 v20, v167 offset:16384
	s_waitcnt lgkmcnt(1)
	v_lshlrev_b32_e32 v19, 16, v19
	s_waitcnt lgkmcnt(0)
	v_lshlrev_b32_e32 v20, 16, v20
	v_mul_f32_e32 v18, v18, v19
	v_cvt_pk_bf16_f32 v18, v18, s0
	ds_write_b16 v167, v18
	v_mul_f32_e32 v18, v21, v20
	v_cvt_pk_bf16_f32 v18, v18, s0
	ds_write_b16 v167, v18 offset:16384
	v_mul_f32_e32 v18, v16, v21
	v_mul_f32_e32 v18, v18, v20
	v_cvt_pk_bf16_f32 v18, v18, s0
	ds_write_b16 v168, v18 offset:32768
	v_add_f32_e32 v18, v28, v17
	v_mul_f32_e32 v18, 0x3fb8aa3b, v18
	v_exp_f32_e64 v21, -v18
	v_exp_f32_e32 v18, v18
	ds_read_u16 v19, v169
	ds_read_u16 v20, v169 offset:16384
	s_waitcnt lgkmcnt(1)
; DEVI u16 f2bf(float f) { return (u16)(cvtpk(f, 0.f) & 0xffffu); }
; DEVI float bf2f(u16 h) { return __uint_as_float(((unsigned)h) << 16); }
; DEVI void gla_seq(const Params& p, int l, int item, char* lds) {
;     ...
; #pragma unroll
;       for (int ii = 0; ii < 16; ++ii) {
;         const int i = seg * 16 + ii;
;         const float bb = bcum[ii] + pre;
;         const int so = i * 256 + (((d >> 3) ^ (i & 7)) << 4) + (d & 7) * 2;
;         const float q = bf2f(*(const u16*)(qs + so)), k = bf2f(*(const u16*)(ks + so));
;         const float eb = __expf(bb), ieb = __frcp_rn(eb);
;         *(u16*)(qs + so) = f2bf(q * eb);
;         *(u16*)(ks + so) = f2bf(k * ieb);
;         *(u16*)(kT + d * 144 + i * 2) = f2bf(k * (etot * ieb));
;       }
;     }
;     __syncthreads();
;     const char* sTc = sT + cur * 16384; char* sTn = sT + (cur ^ 1) * 16384;
;     if (wid < 4) {
	v_lshlrev_b32_e32 v19, 16, v19
	s_waitcnt lgkmcnt(0)
	v_lshlrev_b32_e32 v20, 16, v20
	v_mul_f32_e32 v18, v18, v19
	v_cvt_pk_bf16_f32 v18, v18, s0
	ds_write_b16 v169, v18
	v_mul_f32_e32 v18, v21, v20
	v_cvt_pk_bf16_f32 v18, v18, s0
	ds_write_b16 v169, v18 offset:16384
	v_mul_f32_e32 v18, v16, v21
	v_mul_f32_e32 v18, v18, v20
	v_cvt_pk_bf16_f32 v18, v18, s0
	ds_write_b16 v170, v18 offset:32768
	v_add_f32_e32 v18, v29, v17
	v_mul_f32_e32 v18, 0x3fb8aa3b, v18
	v_exp_f32_e64 v21, -v18
	v_exp_f32_e32 v18, v18
	ds_read_u16 v19, v171
	ds_read_u16 v20, v171 offset:16384
	s_waitcnt lgkmcnt(1)
	v_lshlrev_b32_e32 v19, 16, v19
	s_waitcnt lgkmcnt(0)
	v_lshlrev_b32_e32 v20, 16, v20
	v_mul_f32_e32 v18, v18, v19
	v_cvt_pk_bf16_f32 v18, v18, s0
	ds_write_b16 v171, v18
	v_mul_f32_e32 v18, v21, v20
	v_cvt_pk_bf16_f32 v18, v18, s0
	ds_write_b16 v171, v18 offset:16384
	v_mul_f32_e32 v18, v16, v21
	v_mul_f32_e32 v18, v18, v20
	v_cvt_pk_bf16_f32 v18, v18, s0
	ds_write_b16 v172, v18 offset:32768
	v_add_f32_e32 v18, v30, v17
	v_mul_f32_e32 v18, 0x3fb8aa3b, v18
	v_exp_f32_e64 v21, -v18
	v_exp_f32_e32 v18, v18
	ds_read_u16 v19, v173
	ds_read_u16 v20, v173 offset:16384
	s_waitcnt lgkmcnt(1)
	v_lshlrev_b32_e32 v19, 16, v19
	s_waitcnt lgkmcnt(0)
	v_lshlrev_b32_e32 v20, 16, v20
	v_mul_f32_e32 v18, v18, v19
	v_cvt_pk_bf16_f32 v18, v18, s0
	ds_write_b16 v173, v18
	v_mul_f32_e32 v18, v21, v20
	v_cvt_pk_bf16_f32 v18, v18, s0
	ds_write_b16 v173, v18 offset:16384
	v_mul_f32_e32 v18, v16, v21
	v_mul_f32_e32 v18, v18, v20
	v_cvt_pk_bf16_f32 v18, v18, s0
	ds_write_b16 v174, v18 offset:32768
	v_add_f32_e32 v18, v31, v17
	v_mul_f32_e32 v18, 0x3fb8aa3b, v18
	v_exp_f32_e64 v21, -v18
	v_exp_f32_e32 v18, v18
	ds_read_u16 v19, v175
	ds_read_u16 v20, v175 offset:16384
	s_waitcnt lgkmcnt(1)
	v_lshlrev_b32_e32 v19, 16, v19
	s_waitcnt lgkmcnt(0)
	v_lshlrev_b32_e32 v20, 16, v20
	v_mul_f32_e32 v18, v18, v19
	v_cvt_pk_bf16_f32 v18, v18, s0
	ds_write_b16 v175, v18
	v_mul_f32_e32 v18, v21, v20
	v_cvt_pk_bf16_f32 v18, v18, s0
	ds_write_b16 v175, v18 offset:16384
	v_mul_f32_e32 v18, v16, v21
	v_mul_f32_e32 v18, v18, v20
	v_cvt_pk_bf16_f32 v18, v18, s0
	ds_write_b16 v176, v18 offset:32768
	v_add_f32_e32 v18, v32, v17
	v_mul_f32_e32 v18, 0x3fb8aa3b, v18
	v_exp_f32_e64 v21, -v18
	v_exp_f32_e32 v18, v18
	ds_read_u16 v19, v177
	ds_read_u16 v20, v177 offset:16384
	s_waitcnt lgkmcnt(1)
	v_lshlrev_b32_e32 v19, 16, v19
	s_waitcnt lgkmcnt(0)
	v_lshlrev_b32_e32 v20, 16, v20
	v_mul_f32_e32 v18, v18, v19
	v_cvt_pk_bf16_f32 v18, v18, s0
	ds_write_b16 v177, v18
	v_mul_f32_e32 v18, v21, v20
	v_cvt_pk_bf16_f32 v18, v18, s0
	ds_write_b16 v177, v18 offset:16384
	v_mul_f32_e32 v18, v16, v21
	v_mul_f32_e32 v18, v18, v20
	v_cvt_pk_bf16_f32 v18, v18, s0
	ds_write_b16 v178, v18 offset:32768
	v_add_f32_e32 v18, v33, v17
	v_mul_f32_e32 v18, 0x3fb8aa3b, v18
	v_exp_f32_e64 v21, -v18
	v_exp_f32_e32 v18, v18
	ds_read_u16 v19, v179
	ds_read_u16 v20, v179 offset:16384
	s_waitcnt lgkmcnt(1)
	v_lshlrev_b32_e32 v19, 16, v19
	s_waitcnt lgkmcnt(0)
	v_lshlrev_b32_e32 v20, 16, v20
	v_mul_f32_e32 v18, v18, v19
	v_cvt_pk_bf16_f32 v18, v18, s0
	ds_write_b16 v179, v18
	v_mul_f32_e32 v18, v21, v20
	v_cvt_pk_bf16_f32 v18, v18, s0
	ds_write_b16 v179, v18 offset:16384
	v_mul_f32_e32 v18, v16, v21
	v_mul_f32_e32 v18, v18, v20
	v_cvt_pk_bf16_f32 v18, v18, s0
	ds_write_b16 v180, v18 offset:32768
	v_add_f32_e32 v18, v34, v17
	v_mul_f32_e32 v18, 0x3fb8aa3b, v18
	v_exp_f32_e64 v21, -v18
	v_exp_f32_e32 v18, v18
	ds_read_u16 v19, v181
	ds_read_u16 v20, v181 offset:16384
	v_add_f32_e32 v17, v35, v17
	v_mul_f32_e32 v17, 0x3fb8aa3b, v17
	s_waitcnt lgkmcnt(1)
	v_lshlrev_b32_e32 v19, 16, v19
	s_waitcnt lgkmcnt(0)
	v_lshlrev_b32_e32 v20, 16, v20
	v_exp_f32_e32 v17, v17
	v_mul_f32_e32 v18, v18, v19
	v_cvt_pk_bf16_f32 v18, v18, s0
	ds_write_b16 v181, v18
	v_mul_f32_e32 v18, v21, v20
	v_cvt_pk_bf16_f32 v18, v18, s0
	ds_write_b16 v181, v18 offset:16384
	v_mul_f32_e32 v18, v16, v21
	v_mul_f32_e32 v18, v18, v20
	v_div_scale_f32 v20, s[2:3], v17, v17, 1.0
	v_rcp_f32_e32 v21, v20
	v_cvt_pk_bf16_f32 v18, v18, s0
	ds_write_b16 v182, v18 offset:32768
	ds_read_u16 v18, v183
	ds_read_u16 v19, v183 offset:16384
	v_fma_f32 v22, -v20, v21, 1.0
	v_fmac_f32_e32 v21, v22, v21
	v_div_scale_f32 v22, vcc, 1.0, v17, 1.0
	v_mul_f32_e32 v23, v22, v21
	v_fma_f32 v24, -v20, v23, v22
	v_fmac_f32_e32 v23, v24, v21
	v_fma_f32 v20, -v20, v23, v22
	s_waitcnt lgkmcnt(1)
	v_lshlrev_b32_e32 v18, 16, v18
	v_div_fmas_f32 v20, v20, v21, v23
	v_div_fixup_f32 v20, v20, v17, 1.0
	v_mul_f32_e32 v17, v17, v18
	s_waitcnt lgkmcnt(0)
	v_lshlrev_b32_e32 v19, 16, v19
	v_cvt_pk_bf16_f32 v17, v17, s0
	v_mul_f32_e32 v16, v16, v20
	ds_write_b16 v183, v17
	v_mul_f32_e32 v17, v20, v19
	v_mul_f32_e32 v16, v16, v19
	v_cvt_pk_bf16_f32 v17, v17, s0
	v_cvt_pk_bf16_f32 v16, v16, s0
	ds_write_b16 v183, v17 offset:16384
	ds_write_b16 v184, v16 offset:32768
	s_waitcnt lgkmcnt(0)
	s_barrier
	s_and_saveexec_b64 s[2:3], s[8:9]
	s_cbranch_execz .LBB0_396
; DEVI int crow(int r, int hi) { return (r & 3) + 8 * (r >> 2) + 4 * hi; }
; DEVI void gla_seq(const Params& p, int l, int item, char* lds) {
;     ...
;     if (wid < 4) {
;       f32x16 p0, p1, o;
; #pragma unroll
;       for (int r = 0; r < 16; ++r) { p0[r] = 0.f; p1[r] = 0.f; o[r] = 0.f; }
;       const int irow = iblk * 32 + r32;
; #pragma unroll
;       for (int d0 = 0; d0 < 8; ++d0) {
;         const int chn = d0 * 2 + hi;
;         const bf16x8 b0 = *(const bf16x8*)(ks + r32 * 256 + ((chn ^ (r32 & 7)) << 4));
;         const bf16x8 b1 = *(const bf16x8*)(ks + (32 + r32) * 256 + ((chn ^ (r32 & 7)) << 4));
;         const bf16x8 qf = *(const bf16x8*)(qs + irow * 256 + ((chn ^ (irow & 7)) << 4));
;         p0 = __builtin_amdgcn_mfma_f32_32x32x16_bf16(b0, qf, p0, 0, 0, 0);
;         p1 = __builtin_amdgcn_mfma_f32_32x32x16_bf16(b1, qf, p1, 0, 0, 0);
;       }
; #pragma unroll
;       for (int r = 0; r < 16; ++r) {
;         const int j0 = crow(r, hi), j1 = 32 + j0;
;         const bool k0 = dir ? (j0 < irow) : (j0 <= irow), k1 = dir ? (j1 < irow) : (j1 <= irow);
;         p0[r] = k0 ? p0[r] : 0.f; p1[r] = k1 ? p1[r] : 0.f;
;       }
;       bf16x8 pa0, pa1, pa2, pa3;
;       PK4(p0, 0, pa0); PK4(p0, 8, pa1); PK4(p1, 0, pa2); PK4(p1, 8, pa3);
;       const char* vrow = vT + (eblk * 32 + r32) * 144 + hi * 16;
;       o = __builtin_amdgcn_mfma_f32_32x32x16_bf16(pa0, *(const bf16x8*)(vrow), o, 0, 0, 0);
;       o = __builtin_amdgcn_mfma_f32_32x32x16_bf16(pa1, *(const bf16x8*)(vrow + 32), o, 0, 0, 0);
;       o = __builtin_amdgcn_mfma_f32_32x32x16_bf16(pa2, *(const bf16x8*)(vrow + 64), o, 0, 0, 0);
;       o = __builtin_amdgcn_mfma_f32_32x32x16_bf16(pa3, *(const bf16x8*)(vrow + 96), o, 0, 0, 0);
	v_add_u32_e32 v32, v137, v139
	ds_read_b128 v[16:19], v32 offset:16384
	v_add_u32_e32 v20, v138, v139
	ds_read_b128 v[68:71], v20
	v_add_u32_e32 v80, v137, v140
	ds_read_b128 v[76:79], v80 offset:16384
	ds_read_b128 v[32:35], v32 offset:24576
	v_add_u32_e32 v72, v138, v140
	ds_read_b128 v[72:75], v72
	v_add_u32_e32 v84, v137, v141
	s_waitcnt lgkmcnt(3)
	v_mfma_f32_32x32x16_bf16 v[16:31], v[16:19], v[68:71], 0
	v_add_u32_e32 v88, v137, v142
	v_add_u32_e32 v92, v137, v143
	v_add_u32_e32 v96, v137, v144
	v_add_u32_e32 v188, v137, v145
	v_add_u32_e32 v194, v137, v146
	v_readlane_b32 s68, v254, 30
	v_readlane_b32 s69, v254, 31
	s_waitcnt lgkmcnt(0)
	v_mfma_f32_32x32x16_bf16 v[16:31], v[76:79], v[72:75], v[16:31]
	ds_read_b128 v[76:79], v80 offset:24576
	ds_read_b128 v[80:83], v84 offset:16384
	s_add_i32 s27, s93, 0xffffff00
	s_cmp_lt_u32 s46, 4
	s_cselect_b32 s27, s93, s27
	s_cselect_b32 s29, 0x2000, 0
	v_mfma_f32_32x32x16_bf16 v[32:47], v[32:35], v[68:71], 0
	s_waitcnt lgkmcnt(1)
	v_mfma_f32_32x32x16_bf16 v[32:47], v[76:79], v[72:75], v[32:47]
	v_add_u32_e32 v76, v138, v141
	ds_read_b128 v[76:79], v76
	s_waitcnt lgkmcnt(0)
	v_mfma_f32_32x32x16_bf16 v[16:31], v[80:83], v[76:79], v[16:31]
	ds_read_b128 v[80:83], v84 offset:24576
	ds_read_b128 v[84:87], v88 offset:16384
	s_waitcnt lgkmcnt(1)
	v_mfma_f32_32x32x16_bf16 v[32:47], v[80:83], v[76:79], v[32:47]
	v_add_u32_e32 v80, v138, v142
	ds_read_b128 v[80:83], v80
	s_waitcnt lgkmcnt(0)
	v_mfma_f32_32x32x16_bf16 v[16:31], v[84:87], v[80:83], v[16:31]
	ds_read_b128 v[84:87], v88 offset:24576
	ds_read_b128 v[88:91], v92 offset:16384
	s_waitcnt lgkmcnt(1)
	v_mfma_f32_32x32x16_bf16 v[32:47], v[84:87], v[80:83], v[32:47]
	v_add_u32_e32 v84, v138, v143
	ds_read_b128 v[84:87], v84
	s_waitcnt lgkmcnt(0)
	v_mfma_f32_32x32x16_bf16 v[16:31], v[88:91], v[84:87], v[16:31]
	ds_read_b128 v[88:91], v92 offset:24576
	ds_read_b128 v[92:95], v96 offset:16384
	s_waitcnt lgkmcnt(1)
	v_mfma_f32_32x32x16_bf16 v[32:47], v[88:91], v[84:87], v[32:47]
	v_add_u32_e32 v88, v138, v144
	ds_read_b128 v[88:91], v88
	s_waitcnt lgkmcnt(0)
	v_mfma_f32_32x32x16_bf16 v[16:31], v[92:95], v[88:91], v[16:31]
	ds_read_b128 v[92:95], v96 offset:24576
	ds_read_b128 v[96:99], v188 offset:16384
	s_waitcnt lgkmcnt(1)
	v_mfma_f32_32x32x16_bf16 v[32:47], v[92:95], v[88:91], v[32:47]
	v_add_u32_e32 v92, v138, v145
	ds_read_b128 v[92:95], v92
	s_waitcnt lgkmcnt(0)
	v_mfma_f32_32x32x16_bf16 v[16:31], v[96:99], v[92:95], v[16:31]
	ds_read_b128 v[96:99], v188 offset:24576
	ds_read_b128 v[188:191], v194 offset:16384
	s_waitcnt lgkmcnt(1)
	v_mfma_f32_32x32x16_bf16 v[32:47], v[96:99], v[92:95], v[32:47]
	v_add_u32_e32 v96, v138, v146
	ds_read_b128 v[96:99], v96
	s_waitcnt lgkmcnt(0)
	v_mfma_f32_32x32x16_bf16 v[16:31], v[188:191], v[96:99], v[16:31]
	ds_read_b128 v[188:191], v194 offset:24576
	s_waitcnt lgkmcnt(0)
	v_mfma_f32_32x32x16_bf16 v[32:47], v[188:191], v[96:99], v[32:47]
	s_nop 8
	v_cndmask_b32_e64 v16, 0, v16, s[72:73]
	v_cndmask_b32_e64 v27, 0, v27, s[50:51]
	v_cndmask_b32_e64 v28, 0, v28, s[38:39]
	v_cndmask_b32_e64 v29, 0, v29, s[42:43]
	v_cndmask_b32_e64 v30, 0, v30, s[76:77]
	v_cndmask_b32_e64 v31, 0, v31, s[80:81]
	v_cndmask_b32_e64 v188, 0, v32, s[68:69]
	v_readlane_b32 s68, v254, 32
	v_readlane_b32 s69, v254, 33
	v_cndmask_b32_e64 v199, 0, v42, s[48:49]
	v_cndmask_b32_e64 v200, 0, v43, s[30:31]
	v_cndmask_b32_e64 v17, 0, v17, s[68:69]
	v_readlane_b32 s68, v254, 34
	v_readlane_b32 s69, v254, 35
	v_cvt_pk_bf16_f32 v16, v16, v17
	v_cndmask_b32_e64 v44, 0, v44, s[40:41]
	v_cndmask_b32_e64 v189, 0, v33, s[68:69]
	v_readlane_b32 s68, v254, 36
	v_readlane_b32 s69, v254, 37
	v_cndmask_b32_e64 v45, 0, v45, s[44:45]
	v_cndmask_b32_e64 v46, 0, v46, s[78:79]
	v_cndmask_b32_e64 v18, 0, v18, s[68:69]
	v_readlane_b32 s68, v254, 38
	v_readlane_b32 s69, v254, 39
	v_cndmask_b32_e64 v47, 0, v47, s[82:83]
	s_nop 0
	v_cndmask_b32_e64 v190, 0, v34, s[68:69]
	v_readlane_b32 s68, v254, 40
	v_readlane_b32 s69, v254, 41
	v_cvt_pk_bf16_f32 v34, v28, v29
	s_nop 0
	v_cndmask_b32_e64 v19, 0, v19, s[68:69]
	v_readlane_b32 s68, v254, 42
	v_readlane_b32 s69, v254, 43
	v_cvt_pk_bf16_f32 v17, v18, v19
	s_nop 0
	v_cndmask_b32_e64 v191, 0, v35, s[68:69]
	v_readlane_b32 s68, v254, 44
	v_readlane_b32 s69, v254, 45
	v_cvt_pk_bf16_f32 v35, v30, v31
	s_nop 0
	v_cndmask_b32_e64 v20, 0, v20, s[68:69]
	v_readlane_b32 s68, v254, 46
	v_readlane_b32 s69, v254, 47
	s_nop 1
	v_cndmask_b32_e64 v194, 0, v36, s[68:69]
	v_readlane_b32 s68, v254, 48
	v_readlane_b32 s69, v254, 49
	v_cvt_pk_bf16_f32 v36, v188, v189
	s_nop 0
	v_cndmask_b32_e64 v21, 0, v21, s[68:69]
	v_readlane_b32 s68, v254, 50
	v_readlane_b32 s69, v254, 51
	v_cvt_pk_bf16_f32 v18, v20, v21
	s_nop 1
	v_permlane32_swap_b32_e32 v16, v18
	v_cndmask_b32_e64 v195, 0, v37, s[68:69]
	v_readlane_b32 s68, v254, 52
	v_readlane_b32 s69, v254, 53
	v_cvt_pk_bf16_f32 v37, v190, v191
	s_nop 0
	v_cndmask_b32_e64 v22, 0, v22, s[68:69]
	v_readlane_b32 s68, v254, 54
	v_readlane_b32 s69, v254, 55
	s_nop 1
	v_cndmask_b32_e64 v196, 0, v38, s[68:69]
	v_readlane_b32 s68, v254, 56
	v_readlane_b32 s69, v254, 57
	v_cvt_pk_bf16_f32 v38, v194, v195
	s_nop 1
	v_permlane32_swap_b32_e32 v36, v38
	v_cndmask_b32_e64 v23, 0, v23, s[68:69]
	v_readlane_b32 s68, v254, 58
	v_readlane_b32 s69, v254, 59
	v_cvt_pk_bf16_f32 v19, v22, v23
	s_nop 1
	v_permlane32_swap_b32_e32 v17, v19
	v_cndmask_b32_e64 v39, 0, v39, s[68:69]
	v_readlane_b32 s68, v254, 60
	v_readlane_b32 s69, v254, 61
	ds_read_b128 v[20:23], v187 offset:51200
	v_cvt_pk_bf16_f32 v39, v196, v39
	v_cndmask_b32_e64 v24, 0, v24, s[68:69]
	v_readlane_b32 s68, v254, 62
	v_readlane_b32 s69, v254, 63
	v_permlane32_swap_b32_e32 v37, v39
	s_nop 0
	v_cndmask_b32_e64 v197, 0, v40, s[68:69]
	v_readlane_b32 s68, v255, 0
	v_readlane_b32 s69, v255, 1
	s_nop 1
	v_cndmask_b32_e64 v25, 0, v25, s[68:69]
	v_readlane_b32 s68, v255, 2
	v_readlane_b32 s69, v255, 3
	v_cvt_pk_bf16_f32 v32, v24, v25
	s_nop 1
	v_permlane32_swap_b32_e32 v32, v34
	v_cndmask_b32_e64 v198, 0, v41, s[68:69]
	v_readlane_b32 s68, v255, 4
	v_readlane_b32 s69, v255, 5
	ds_read_b128 v[40:43], v187 offset:51232
	s_nop 0
	v_cndmask_b32_e64 v26, 0, v26, s[68:69]
	v_cvt_pk_bf16_f32 v33, v26, v27
	s_waitcnt lgkmcnt(1)
; DEVI u16 f2bf(float f) { return (u16)(cvtpk(f, 0.f) & 0xffffu); }
; DEVI int crow(int r, int hi) { return (r & 3) + 8 * (r >> 2) + 4 * hi; }
; DEVI void gla_seq(const Params& p, int l, int item, char* lds) {
;     ...
;       const char* vrow = vT + (eblk * 32 + r32) * 144 + hi * 16;
;       o = __builtin_amdgcn_mfma_f32_32x32x16_bf16(pa0, *(const bf16x8*)(vrow), o, 0, 0, 0);
;       o = __builtin_amdgcn_mfma_f32_32x32x16_bf16(pa1, *(const bf16x8*)(vrow + 32), o, 0, 0, 0);
;       o = __builtin_amdgcn_mfma_f32_32x32x16_bf16(pa2, *(const bf16x8*)(vrow + 64), o, 0, 0, 0);
;       o = __builtin_amdgcn_mfma_f32_32x32x16_bf16(pa3, *(const bf16x8*)(vrow + 96), o, 0, 0, 0);
;       const int erow = eblk * 32 + r32;
; #pragma unroll
;       for (int d0 = 0; d0 < 8; ++d0) {
;         const int chn = d0 * 2 + hi;
;         const bf16x8 qf = *(const bf16x8*)(qs + irow * 256 + ((chn ^ (irow & 7)) << 4));
;         const bf16x8 sf = *(const bf16x8*)(sTc + erow * 256 + ((chn ^ (erow & 7)) << 4));
;         o = __builtin_amdgcn_mfma_f32_32x32x16_bf16(qf, sf, o, 0, 0, 0);
;       }
; #pragma unroll
;       for (int r = 0; r < 16; ++r)
;         og[gla_row(bi, dir, cc, iblk * 32 + crow(r, hi)) * 1024 + h * 256 + sl * 64 + eblk * 32 + r32] = f2bf(o[r]);
	v_mfma_f32_32x32x16_bf16 v[16:31], v[16:19], v[20:23], 0
	v_permlane32_swap_b32_e32 v33, v35
	v_readlane_b32 s68, v253, 21
	s_waitcnt lgkmcnt(0)
	v_mfma_f32_32x32x16_bf16 v[16:31], v[32:35], v[40:43], v[16:31]
	ds_read_b128 v[40:43], v187 offset:51264
	v_cvt_pk_bf16_f32 v32, v197, v198
	v_cvt_pk_bf16_f32 v33, v199, v200
	v_cvt_pk_bf16_f32 v34, v44, v45
	v_cvt_pk_bf16_f32 v35, v46, v47
	s_nop 0
	v_permlane32_swap_b32_e32 v32, v34
	s_waitcnt lgkmcnt(0)
	v_mfma_f32_32x32x16_bf16 v[16:31], v[36:39], v[40:43], v[16:31]
	v_permlane32_swap_b32_e32 v33, v35
	ds_read_b128 v[36:39], v187 offset:51296
	s_waitcnt lgkmcnt(0)
	v_mfma_f32_32x32x16_bf16 v[16:31], v[32:35], v[36:39], v[16:31]
	v_lshl_add_u32 v36, s75, 14, v134
	v_add_u32_e32 v32, v36, v139
	ds_read_b128 v[32:35], v32 offset:60416
	s_waitcnt lgkmcnt(0)
	v_mfma_f32_32x32x16_bf16 v[16:31], v[68:71], v[32:35], v[16:31]
	v_add_u32_e32 v32, v36, v140
	ds_read_b128 v[32:35], v32 offset:60416
	s_waitcnt lgkmcnt(0)
	v_mfma_f32_32x32x16_bf16 v[16:31], v[72:75], v[32:35], v[16:31]
	v_add_u32_e32 v32, v36, v141
	ds_read_b128 v[32:35], v32 offset:60416
	s_waitcnt lgkmcnt(0)
	v_mfma_f32_32x32x16_bf16 v[16:31], v[76:79], v[32:35], v[16:31]
	v_add_u32_e32 v32, v36, v142
	ds_read_b128 v[32:35], v32 offset:60416
	s_waitcnt lgkmcnt(0)
	v_mfma_f32_32x32x16_bf16 v[16:31], v[80:83], v[32:35], v[16:31]
	v_add_u32_e32 v32, v36, v143
	ds_read_b128 v[32:35], v32 offset:60416
	s_waitcnt lgkmcnt(0)
	v_mfma_f32_32x32x16_bf16 v[16:31], v[84:87], v[32:35], v[16:31]
	v_add_u32_e32 v32, v36, v144
	ds_read_b128 v[32:35], v32 offset:60416
	s_waitcnt lgkmcnt(0)
	v_mfma_f32_32x32x16_bf16 v[16:31], v[88:91], v[32:35], v[16:31]
	v_add_u32_e32 v32, v36, v145
	ds_read_b128 v[32:35], v32 offset:60416
	v_add_u32_e32 v36, v36, v146
	ds_read_b128 v[36:39], v36 offset:60416
	s_waitcnt lgkmcnt(1)
	v_mfma_f32_32x32x16_bf16 v[16:31], v[92:95], v[32:35], v[16:31]
	v_or_b32_e32 v34, s27, v151
	s_cselect_b32 s27, 0xff, s61
	v_sub_u32_e32 v32, s27, v34
	s_add_i32 s29, s29, s68
	v_cndmask_b32_e64 v32, v32, v34, s[4:5]
	v_add_u32_e32 v32, s29, v32
	v_ashrrev_i32_e32 v33, 31, v32
	s_waitcnt lgkmcnt(0)
; DEVI u16 f2bf(float f) { return (u16)(cvtpk(f, 0.f) & 0xffffu); }
; DEVI int crow(int r, int hi) { return (r & 3) + 8 * (r >> 2) + 4 * hi; }
; DEVI long gla_row(int bi, int dir, int cc, int i) {
;   const int L = (cc < 4) ? CTXL : SEQ, c = (cc < 4) ? cc : cc - 4, rb = bi * ROWS + ((cc < 4) ? SEQ : 0);
;   const int tl = c * 64 + i;
;   return (long)(rb + (dir ? (L - 1 - tl) : tl));
; }
; DEVI void gla_seq(const Params& p, int l, int item, char* lds) {
;     ...
; #pragma unroll
;       for (int r = 0; r < 16; ++r)
;         og[gla_row(bi, dir, cc, iblk * 32 + crow(r, hi)) * 1024 + h * 256 + sl * 64 + eblk * 32 + r32] = f2bf(o[r]);
	v_mfma_f32_32x32x16_bf16 v[16:31], v[96:99], v[36:39], v[16:31]
	v_lshlrev_b64 v[32:33], 11, v[32:33]
	v_lshl_add_u64 v[32:33], v[102:103], 0, v[32:33]
	s_nop 9
	v_cvt_pk_bf16_f32 v16, v16, s0
	global_store_short v[32:33], v16, off
	v_or_b32_e32 v16, 1, v34
	v_cvt_pk_bf16_f32 v32, v17, s0
	v_sub_u32_e32 v17, s27, v16
	v_cndmask_b32_e64 v16, v17, v16, s[4:5]
	v_add_u32_e32 v16, s29, v16
	v_ashrrev_i32_e32 v17, 31, v16
	v_lshlrev_b64 v[16:17], 11, v[16:17]
	v_lshl_add_u64 v[16:17], v[102:103], 0, v[16:17]
	global_store_short v[16:17], v32, off
	v_or_b32_e32 v16, 2, v34
	v_sub_u32_e32 v17, s27, v16
	v_cndmask_b32_e64 v16, v17, v16, s[4:5]
	v_add_u32_e32 v16, s29, v16
	v_ashrrev_i32_e32 v17, 31, v16
	v_lshlrev_b64 v[16:17], 11, v[16:17]
	v_cvt_pk_bf16_f32 v18, v18, s0
	v_lshl_add_u64 v[16:17], v[102:103], 0, v[16:17]
	global_store_short v[16:17], v18, off
	v_or_b32_e32 v16, 3, v34
	v_sub_u32_e32 v17, s27, v16
	v_cndmask_b32_e64 v16, v17, v16, s[4:5]
	v_add_u32_e32 v16, s29, v16
	v_ashrrev_i32_e32 v17, 31, v16
	v_lshlrev_b64 v[16:17], 11, v[16:17]
	v_cvt_pk_bf16_f32 v18, v19, s0
	v_lshl_add_u64 v[16:17], v[102:103], 0, v[16:17]
	global_store_short v[16:17], v18, off
	v_or_b32_e32 v16, 8, v34
	v_sub_u32_e32 v17, s27, v16
	v_cndmask_b32_e64 v16, v17, v16, s[4:5]
	v_add_u32_e32 v16, s29, v16
	v_ashrrev_i32_e32 v17, 31, v16
	v_lshlrev_b64 v[16:17], 11, v[16:17]
	v_cvt_pk_bf16_f32 v18, v20, s0
	v_lshl_add_u64 v[16:17], v[102:103], 0, v[16:17]
	global_store_short v[16:17], v18, off
	v_or_b32_e32 v16, 9, v34
	v_sub_u32_e32 v17, s27, v16
	v_cndmask_b32_e64 v16, v17, v16, s[4:5]
	v_add_u32_e32 v16, s29, v16
	v_ashrrev_i32_e32 v17, 31, v16
	v_lshlrev_b64 v[16:17], 11, v[16:17]
	v_cvt_pk_bf16_f32 v18, v21, s0
	v_lshl_add_u64 v[16:17], v[102:103], 0, v[16:17]
	global_store_short v[16:17], v18, off
	v_or_b32_e32 v16, 10, v34
	v_sub_u32_e32 v17, s27, v16
	v_cndmask_b32_e64 v16, v17, v16, s[4:5]
	v_add_u32_e32 v16, s29, v16
	v_ashrrev_i32_e32 v17, 31, v16
	v_lshlrev_b64 v[16:17], 11, v[16:17]
	v_cvt_pk_bf16_f32 v18, v22, s0
	v_lshl_add_u64 v[16:17], v[102:103], 0, v[16:17]
	global_store_short v[16:17], v18, off
	v_or_b32_e32 v16, 11, v34
	v_sub_u32_e32 v17, s27, v16
	v_cndmask_b32_e64 v16, v17, v16, s[4:5]
	v_add_u32_e32 v16, s29, v16
	v_ashrrev_i32_e32 v17, 31, v16
	v_lshlrev_b64 v[16:17], 11, v[16:17]
	v_cvt_pk_bf16_f32 v18, v23, s0
	v_lshl_add_u64 v[16:17], v[102:103], 0, v[16:17]
	global_store_short v[16:17], v18, off
	v_or_b32_e32 v16, 16, v34
	v_sub_u32_e32 v17, s27, v16
	v_cndmask_b32_e64 v16, v17, v16, s[4:5]
	v_add_u32_e32 v16, s29, v16
	v_ashrrev_i32_e32 v17, 31, v16
	v_lshlrev_b64 v[16:17], 11, v[16:17]
	v_cvt_pk_bf16_f32 v18, v24, s0
	v_lshl_add_u64 v[16:17], v[102:103], 0, v[16:17]
	global_store_short v[16:17], v18, off
	v_or_b32_e32 v16, 17, v34
	v_sub_u32_e32 v17, s27, v16
	v_cndmask_b32_e64 v16, v17, v16, s[4:5]
	v_add_u32_e32 v16, s29, v16
	v_ashrrev_i32_e32 v17, 31, v16
	v_lshlrev_b64 v[16:17], 11, v[16:17]
	v_cvt_pk_bf16_f32 v18, v25, s0
	v_lshl_add_u64 v[16:17], v[102:103], 0, v[16:17]
	global_store_short v[16:17], v18, off
	v_or_b32_e32 v16, 18, v34
	v_sub_u32_e32 v17, s27, v16
	v_cndmask_b32_e64 v16, v17, v16, s[4:5]
	v_add_u32_e32 v16, s29, v16
	v_ashrrev_i32_e32 v17, 31, v16
	v_lshlrev_b64 v[16:17], 11, v[16:17]
	v_cvt_pk_bf16_f32 v18, v26, s0
	v_lshl_add_u64 v[16:17], v[102:103], 0, v[16:17]
	global_store_short v[16:17], v18, off
	v_or_b32_e32 v16, 19, v34
	v_sub_u32_e32 v17, s27, v16
	v_cndmask_b32_e64 v16, v17, v16, s[4:5]
	v_add_u32_e32 v16, s29, v16
	v_ashrrev_i32_e32 v17, 31, v16
	v_lshlrev_b64 v[16:17], 11, v[16:17]
	v_cvt_pk_bf16_f32 v18, v27, s0
	v_lshl_add_u64 v[16:17], v[102:103], 0, v[16:17]
	global_store_short v[16:17], v18, off
	v_or_b32_e32 v16, 24, v34
	v_sub_u32_e32 v17, s27, v16
	v_cndmask_b32_e64 v16, v17, v16, s[4:5]
	v_add_u32_e32 v16, s29, v16
	v_ashrrev_i32_e32 v17, 31, v16
	v_lshlrev_b64 v[16:17], 11, v[16:17]
	v_cvt_pk_bf16_f32 v18, v28, s0
	v_lshl_add_u64 v[16:17], v[102:103], 0, v[16:17]
	global_store_short v[16:17], v18, off
	v_or_b32_e32 v16, 25, v34
	v_sub_u32_e32 v17, s27, v16
	v_cndmask_b32_e64 v16, v17, v16, s[4:5]
	v_add_u32_e32 v16, s29, v16
	v_ashrrev_i32_e32 v17, 31, v16
	v_lshlrev_b64 v[16:17], 11, v[16:17]
	v_cvt_pk_bf16_f32 v18, v29, s0
	v_lshl_add_u64 v[16:17], v[102:103], 0, v[16:17]
	global_store_short v[16:17], v18, off
	v_or_b32_e32 v16, 26, v34
	v_sub_u32_e32 v17, s27, v16
	v_cndmask_b32_e64 v16, v17, v16, s[4:5]
	v_add_u32_e32 v16, s29, v16
	v_ashrrev_i32_e32 v17, 31, v16
	v_lshlrev_b64 v[16:17], 11, v[16:17]
	v_cvt_pk_bf16_f32 v18, v30, s0
	v_lshl_add_u64 v[16:17], v[102:103], 0, v[16:17]
	global_store_short v[16:17], v18, off
	v_or_b32_e32 v16, 27, v34
	v_sub_u32_e32 v17, s27, v16
	v_cndmask_b32_e64 v16, v17, v16, s[4:5]
	v_add_u32_e32 v16, s29, v16
	v_ashrrev_i32_e32 v17, 31, v16
	v_lshlrev_b64 v[16:17], 11, v[16:17]
	v_cvt_pk_bf16_f32 v18, v31, s0
	v_lshl_add_u64 v[16:17], v[102:103], 0, v[16:17]
	global_store_short v[16:17], v18, off
	s_branch .LBB0_396
